# GEMM<2>: epilogue LDS patches relocated behind the first-k-tile staging slots (0x18020..) and the tile-start barrier removed
# speedup vs baseline: 1.0079x; 1.0079x over previous
.LBB0_289:
	s_andn2_b64 vcc, exec, s[0:1]
	s_cbranch_vccnz .LBB0_888
	v_readlane_b32 s0, v251, 20
	v_mov_b32_e32 v0, v179
	v_readlane_b32 s1, v251, 21
	s_load_dword s10, s[0:1], 0x0
	v_readlane_b32 s1, v251, 24
	v_lshrrev_b32_e32 v8, 4, v0
	v_xor_b32_e32 v8, v8, v0
	v_readlane_b32 s2, v253, 36
	s_waitcnt lgkmcnt(0)
	s_lshr_b32 s0, s10, 3
	s_mul_i32 s0, s0, s1
	v_readlane_b32 s1, v251, 25
	s_add_i32 s0, s0, s1
	s_and_b32 s1, s10, 7
	s_cmp_eq_u32 s1, 0
	v_lshlrev_b32_e32 v8, 3, v8
	v_add_u32_e32 v10, 0x200, v0
	v_ashrrev_i32_e32 v2, 6, v0
	v_lshrrev_b32_e32 v3, 5, v0
	v_bfe_u32 v4, v0, 5, 1
	v_ashrrev_i32_e32 v5, 8, v0
	v_bfe_u32 v7, v0, 1, 3
	s_cselect_b32 s12, s0, s2
	v_and_b32_e32 v8, 56, v8
	v_lshlrev_b32_e32 v9, 7, v0
	s_movk_i32 s0, 0xfc00
	v_lshlrev_b32_e32 v143, 4, v0
	v_lshlrev_b32_e32 v11, 7, v10
	v_lshlrev_b32_e32 v145, 4, v10
	v_add_u32_e32 v10, 0x400, v0
	v_add_u32_e32 v0, 0x600, v0
	v_and_or_b32 v144, v11, s0, v8
	v_lshlrev_b32_e32 v11, 7, v10
	v_lshlrev_b32_e32 v147, 4, v10
	v_lshlrev_b32_e32 v10, 7, v0
	v_and_b32_e32 v6, 3, v2
	v_and_or_b32 v142, v9, s0, v8
	v_and_or_b32 v146, v11, s0, v8
	v_and_or_b32 v148, v10, s0, v8
	v_lshlrev_b32_e32 v149, 4, v0
	v_lshlrev_b32_e32 v0, 14, v5
	v_and_b32_e32 v8, 0xf80, v9
	v_add3_u32 v150, 32, v0, v8
	v_lshlrev_b32_e32 v0, 13, v6
	v_readlane_b32 s0, v254, 3
	s_mov_b32 s11, 0
	v_lshlrev_b32_e32 v153, 7, v5
	v_add3_u32 v151, s0, v0, v8
	v_bitop3_b32 v0, v3, v7, 1 bitop3:0x6c
	s_movk_i32 s0, 0x1200
	v_lshlrev_b32_e32 v152, 4, v0
	v_mul_lo_u32 v0, v2, s0
	v_add_u32_e32 v155, 0x18020, v0
	v_bitop3_b32 v0, v4, v7, 2 bitop3:0x36
	v_lshlrev_b32_e32 v156, 4, v0
	v_bitop3_b32 v0, v4, v7, 4 bitop3:0x36
	v_lshlrev_b32_e32 v157, 4, v0
	v_bitop3_b32 v0, v4, v7, 6 bitop3:0x36
	v_lshlrev_b32_e32 v154, 6, v6
	v_lshlrev_b32_e32 v158, 4, v0
	v_readlane_b32 s3, v253, 37
	s_branch .LBB0_293

.LBB0_293:
	s_add_i32 s2, s11, s12
	s_cmpk_gt_i32 s2, 0xcb1
	s_mov_b64 s[0:1], -1
	s_cbranch_scc1 .LBB0_292
	s_mul_hi_i32 s0, s2, 0x51eb851f
	s_lshr_b32 s1, s0, 31
	s_ashr_i32 s0, s0, 6
	s_add_i32 s0, s0, s1
	s_lshl_b32 s1, s0, 3
	s_sub_i32 s3, 0x82, s1
	s_min_u32 s3, s3, 8
	v_cvt_f32_ubyte0_e32 v0, s3
	v_rcp_iflag_f32_e32 v0, v0
	s_sub_i32 s5, 0, s3
	s_mulk_i32 s0, 0xff38
	s_add_i32 s0, s0, s2
	v_mul_f32_e32 v0, 0x4f7ffffe, v0
	v_cvt_u32_f32_e32 v0, v0
	s_abs_i32 s4, s0
	s_ashr_i32 s2, s0, 31
	v_readlane_b32 s16, v251, 2
	v_readfirstlane_b32 s7, v0
	s_mul_i32 s5, s5, s7
	s_mul_hi_u32 s5, s7, s5
	s_add_i32 s7, s7, s5
	s_mul_hi_u32 s5, s4, s7
	s_mul_i32 s7, s5, s3
	s_sub_i32 s4, s4, s7
	s_add_i32 s7, s5, 1
	s_sub_i32 s8, s4, s3
	s_cmp_ge_u32 s4, s3
	s_cselect_b32 s5, s7, s5
	s_cselect_b32 s4, s8, s4
	s_add_i32 s7, s5, 1
	s_cmp_ge_u32 s4, s3
	s_cselect_b32 s4, s7, s5
	s_xor_b32 s4, s4, s2
	s_sub_i32 s4, s4, s2
	s_mul_i32 s2, s4, s3
	s_sub_i32 s0, s0, s2
	s_add_i32 s0, s0, s1
	s_lshl_b32 s0, s0, 8
	s_lshl_b32 s4, s4, 8
	s_ashr_i32 s1, s0, 31
	s_ashr_i32 s5, s4, 31
	s_lshl_b64 s[2:3], s[0:1], 11
	s_lshl_b64 s[8:9], s[4:5], 11
	v_readlane_b32 s28, v251, 14
	v_readlane_b32 s29, v251, 15
	s_add_u32 s14, s28, s2
	v_mov_b32_e32 v0, v142
	s_addc_u32 s15, s29, s3
	s_waitcnt vmcnt(63) expcnt(7) lgkmcnt(15)
	s_nop 0
	v_readlane_b32 s17, v251, 3
	v_lshl_add_u64 v[2:3], v[0:1], 1, s[14:15]
	v_add_u32_e32 v0, 32, v143
	v_readlane_b32 s16, v251, 42
	v_readfirstlane_b32 s1, v0
	s_mov_b32 m0, s1
	v_mov_b32_e32 v0, v144
	global_load_lds_dwordx4 v[2:3], off
	v_readlane_b32 s17, v251, 43
	v_lshl_add_u64 v[2:3], v[0:1], 1, s[14:15]
	v_add_u32_e32 v0, 32, v145
	s_add_u32 s16, s16, s8
	v_readfirstlane_b32 s1, v0
	s_mov_b32 m0, s1
	v_mov_b32_e32 v0, v146
	global_load_lds_dwordx4 v[2:3], off
	s_addc_u32 s17, s17, s9
	v_lshl_add_u64 v[2:3], v[0:1], 1, s[14:15]
	v_add_u32_e32 v0, 32, v147
	v_readlane_b32 s5, v254, 3
	v_readfirstlane_b32 s1, v0
	s_mov_b32 m0, s1
	v_mov_b32_e32 v0, v148
	global_load_lds_dwordx4 v[2:3], off
	s_mov_b32 s6, 0
	v_lshl_add_u64 v[2:3], v[0:1], 1, s[14:15]
	v_add_u32_e32 v0, 32, v149
	v_readlane_b32 s18, v251, 4
	v_readfirstlane_b32 s1, v0
	s_mov_b32 m0, s1
	v_mov_b32_e32 v0, v142
	global_load_lds_dwordx4 v[2:3], off
	v_readlane_b32 s19, v251, 5
	v_lshl_add_u64 v[2:3], v[0:1], 1, s[16:17]
	v_add_u32_e32 v0, s5, v143
	v_readlane_b32 s20, v251, 6
	v_readfirstlane_b32 s1, v0
	s_mov_b32 m0, s1
	v_mov_b32_e32 v0, v144
	global_load_lds_dwordx4 v[2:3], off
	v_readlane_b32 s21, v251, 7
	v_lshl_add_u64 v[2:3], v[0:1], 1, s[16:17]
	v_add_u32_e32 v0, s5, v145
	v_readlane_b32 s22, v251, 8
	v_readfirstlane_b32 s1, v0
	s_mov_b32 m0, s1
	v_mov_b32_e32 v0, v146
	global_load_lds_dwordx4 v[2:3], off
	v_readlane_b32 s23, v251, 9
	v_lshl_add_u64 v[2:3], v[0:1], 1, s[16:17]
	v_add_u32_e32 v0, s5, v147
	v_readlane_b32 s24, v251, 10
	v_readfirstlane_b32 s1, v0
	s_mov_b32 m0, s1
	v_mov_b32_e32 v0, v148
	global_load_lds_dwordx4 v[2:3], off
	v_readlane_b32 s25, v251, 11
	v_lshl_add_u64 v[2:3], v[0:1], 1, s[16:17]
	v_add_u32_e32 v0, s5, v149
	v_readlane_b32 s26, v251, 12
	v_readfirstlane_b32 s1, v0
	s_mov_b32 m0, s1
	v_readlane_b32 s1, v253, 29
	global_load_lds_dwordx4 v[2:3], off
	s_add_u32 s1, s1, s2
	v_readlane_b32 s2, v253, 30
	s_waitcnt vmcnt(0)
	s_addc_u32 s5, s2, s3
	v_readlane_b32 s2, v253, 31
	s_add_u32 s7, s2, s8
	v_readlane_b32 s2, v253, 32
	v_mov_b32_e32 v2, 0
	s_addc_u32 s8, s2, s9
	s_mov_b64 s[2:3], 0
	v_mov_b32_e32 v3, v2
	v_mov_b32_e32 v4, v2
	v_mov_b32_e32 v5, v2
	v_mov_b32_e32 v6, v2
	v_mov_b32_e32 v7, v2
	v_mov_b32_e32 v8, v2
	v_mov_b32_e32 v9, v2
	v_mov_b32_e32 v10, v2
	v_mov_b32_e32 v11, v2
	v_mov_b32_e32 v12, v2
	v_mov_b32_e32 v13, v2
	s_waitcnt vmcnt(0)
	v_mov_b32_e32 v14, v2
	v_mov_b32_e32 v15, v2
	v_mov_b32_e32 v16, v2
	v_mov_b32_e32 v17, v2
	v_mov_b32_e32 v18, v2
	v_mov_b32_e32 v19, v2
	v_mov_b32_e32 v20, v2
	v_mov_b32_e32 v21, v2
	v_mov_b32_e32 v22, v2
	v_mov_b32_e32 v23, v2
	v_mov_b32_e32 v24, v2
	v_mov_b32_e32 v25, v2
	v_mov_b32_e32 v26, v2
	v_mov_b32_e32 v27, v2
	v_mov_b32_e32 v28, v2
	v_mov_b32_e32 v29, v2
	v_mov_b32_e32 v30, v2
	v_mov_b32_e32 v31, v2
	v_mov_b32_e32 v32, v2
	v_mov_b32_e32 v33, v2
	v_mov_b32_e32 v34, v2
	v_mov_b32_e32 v35, v2
	v_mov_b32_e32 v36, v2
	v_mov_b32_e32 v37, v2
	v_mov_b32_e32 v38, v2
	v_mov_b32_e32 v39, v2
	v_mov_b32_e32 v40, v2
	v_mov_b32_e32 v41, v2
	v_mov_b32_e32 v42, v2
	v_mov_b32_e32 v43, v2
	v_mov_b32_e32 v44, v2
	v_mov_b32_e32 v45, v2
	v_mov_b32_e32 v46, v2
	v_mov_b32_e32 v47, v2
	v_mov_b32_e32 v48, v2
	v_mov_b32_e32 v49, v2
	v_mov_b32_e32 v50, v2
	v_mov_b32_e32 v51, v2
	v_mov_b32_e32 v52, v2
	v_mov_b32_e32 v53, v2
	v_mov_b32_e32 v54, v2
	v_mov_b32_e32 v55, v2
	v_mov_b32_e32 v56, v2
	v_mov_b32_e32 v57, v2
	v_mov_b32_e32 v58, v2
	v_mov_b32_e32 v59, v2
	v_mov_b32_e32 v60, v2
	v_mov_b32_e32 v61, v2
	v_mov_b32_e32 v62, v2
	v_mov_b32_e32 v63, v2
	v_mov_b32_e32 v64, v2
	v_mov_b32_e32 v65, v2
	v_mov_b32_e32 v66, v2
	v_mov_b32_e32 v67, v2
	v_mov_b32_e32 v68, v2
	v_mov_b32_e32 v69, v2
	v_mov_b32_e32 v70, v2
	v_mov_b32_e32 v71, v2
	v_mov_b32_e32 v72, v2
	v_mov_b32_e32 v73, v2
	v_mov_b32_e32 v74, v2
	v_mov_b32_e32 v75, v2
	v_mov_b32_e32 v76, v2
	v_mov_b32_e32 v77, v2
	v_mov_b32_e32 v78, v2
	v_mov_b32_e32 v79, v2
	v_mov_b32_e32 v80, v2
	v_mov_b32_e32 v81, v2
	v_mov_b32_e32 v82, v2
	v_mov_b32_e32 v83, v2
	v_mov_b32_e32 v84, v2
	v_mov_b32_e32 v85, v2
	v_mov_b32_e32 v86, v2
	v_mov_b32_e32 v87, v2
	v_mov_b32_e32 v88, v2
	v_mov_b32_e32 v89, v2
	v_mov_b32_e32 v90, v2
	v_mov_b32_e32 v91, v2
	v_mov_b32_e32 v92, v2
	v_mov_b32_e32 v93, v2
	v_mov_b32_e32 v94, v2
	v_mov_b32_e32 v95, v2
	v_mov_b32_e32 v96, v2
	v_mov_b32_e32 v97, v2
	v_mov_b32_e32 v98, v2
	v_mov_b32_e32 v99, v2
	v_mov_b32_e32 v100, v2
	v_mov_b32_e32 v101, v2
	v_mov_b32_e32 v102, v2
	v_mov_b32_e32 v103, v2
	v_mov_b32_e32 v104, v2
	v_mov_b32_e32 v105, v2
	v_mov_b32_e32 v106, v2
	v_mov_b32_e32 v107, v2
	v_mov_b32_e32 v108, v2
	v_mov_b32_e32 v109, v2
	v_mov_b32_e32 v110, v2
	v_mov_b32_e32 v111, v2
	v_mov_b32_e32 v112, v2
	v_mov_b32_e32 v113, v2
	v_mov_b32_e32 v114, v2
	v_mov_b32_e32 v115, v2
	v_mov_b32_e32 v116, v2
	v_mov_b32_e32 v117, v2
	v_mov_b32_e32 v118, v2
	v_mov_b32_e32 v119, v2
	v_mov_b32_e32 v120, v2
	v_mov_b32_e32 v121, v2
	v_mov_b32_e32 v122, v2
	v_mov_b32_e32 v123, v2
	v_mov_b32_e32 v124, v2
	v_mov_b32_e32 v125, v2
	v_mov_b32_e32 v126, v2
	v_mov_b32_e32 v127, v2
	v_mov_b32_e32 v128, v2
	v_mov_b32_e32 v129, v2
	v_readlane_b32 s27, v251, 13
	v_readlane_b32 s30, v251, 16
	v_readlane_b32 s31, v251, 17
	s_waitcnt lgkmcnt(0)
	s_barrier
	v_lshlrev_b32_e32 v159, 1, v142
	v_readfirstlane_b32 s9, v143
	v_add_u32_e32 v177, v150, v152
	v_add_u32_e32 v207, v151, v152
	v_add_u32_e32 v204, v150, v156
	v_add_u32_e32 v208, v151, v156
	v_add_u32_e32 v205, v150, v157
	v_add_u32_e32 v209, v151, v157
	v_add_u32_e32 v206, v150, v158
	v_add_u32_e32 v210, v151, v158
	s_mov_b32 s6, 7
	v_readfirstlane_b32 s66, v179
	s_cmp_ge_u32 s66, 0x100
	s_cbranch_scc0 .Lg295_np
	s_setprio 1
